# on top of v29: the 16 packed v_pk_add_f32 of the forgetting-attention pipelined step (row sums beside the PV MFMAs) split into scalar v_add_f32 pairs
# baseline (speedup 1.0000x reference)
.LBB0_887:
	s_andn2_b64 vcc, exec, s[4:5]
	s_cbranch_vccnz .LBB0_889
	v_add_u32_e32 v246, s33, v202
	v_add_u32_e32 v246, 0x18a00, v246
	s_nop 6
	v_add_u32_e32 v0, s58, v197
	v_add_u32_e32 v247, s58, v195
	ds_read_b128 v[66:69], v247
	ds_read_b128 v[70:73], v247 offset:4096
	v_add_u32_e32 v248, s58, v198
	ds_read_b128 v[74:77], v248
	ds_read_b128 v[78:81], v248 offset:4096
	v_add_u32_e32 v249, s58, v199
	ds_read_b128 v[82:85], v249
	ds_read_b128 v[86:89], v249 offset:4096
	v_add_u32_e32 v250, s58, v200
	ds_read_b128 v[90:93], v250
	ds_read_b128 v[94:97], v250 offset:4096
	ds_read_b128 v[34:37], v246 offset:256
	ds_read_b128 v[50:53], v246 offset:384
	ds_read_b128 v[38:41], v246 offset:288
	ds_read_b128 v[54:57], v246 offset:416
	ds_read_b128 v[42:45], v246 offset:320
	ds_read_b128 v[58:61], v246 offset:448
	ds_read_b128 v[46:49], v246 offset:352
	ds_read_b128 v[62:65], v246 offset:480
	s_waitcnt lgkmcnt(1)
	v_mfma_f32_32x32x16_bf16 v[34:49], v[66:69], v[146:149], v[34:49]
	s_waitcnt lgkmcnt(0)
	v_mfma_f32_32x32x16_bf16 v[50:65], v[70:73], v[146:149], v[50:65]
	v_mfma_f32_32x32x16_bf16 v[34:49], v[74:77], v[150:153], v[34:49]
	v_mfma_f32_32x32x16_bf16 v[50:65], v[78:81], v[150:153], v[50:65]
	v_mfma_f32_32x32x16_bf16 v[34:49], v[82:85], v[154:157], v[34:49]
	v_mfma_f32_32x32x16_bf16 v[50:65], v[86:89], v[154:157], v[50:65]
	v_mfma_f32_32x32x16_bf16 v[34:49], v[90:93], v[158:161], v[34:49]
	v_mfma_f32_32x32x16_bf16 v[50:65], v[94:97], v[158:161], v[50:65]
	s_add_i32 s4, s58, 0x2000
	ds_read_b128 v[82:85], v247 offset:8192
	ds_read_b128 v[66:69], v246
	ds_read_b128 v[70:73], v246 offset:32
	ds_read_b128 v[74:77], v246 offset:64
	ds_read_b128 v[78:81], v246 offset:96
	s_nop 5
	v_exp_f32_e32 v162, v50
	v_exp_f32_e32 v138, v51
	v_exp_f32_e32 v130, v52
	s_waitcnt lgkmcnt(0)
	v_mfma_f32_32x32x16_bf16 v[66:81], v[82:85], v[146:149], v[66:81]
	ds_read_b128 v[82:85], v248 offset:8192
	ds_read_b128 v[86:89], v250 offset:8192
	v_exp_f32_e32 v122, v34
	v_exp_f32_e32 v134, v35
	v_exp_f32_e32 v126, v36
	v_exp_f32_e32 v116, v37
	s_waitcnt lgkmcnt(1)
	v_mfma_f32_32x32x16_bf16 v[66:81], v[82:85], v[150:153], v[66:81]
	ds_read_b128 v[82:85], v249 offset:8192
	ds_read_b128 v[34:37], v247 offset:12288
	ds_read_b128 v[90:93], v246 offset:192
	ds_read_b128 v[94:97], v246 offset:224
	v_exp_f32_e32 v172, v53
	v_exp_f32_e32 v186, v38
	v_exp_f32_e32 v168, v39
	s_waitcnt lgkmcnt(3)
	v_mfma_f32_32x32x16_bf16 v[66:81], v[82:85], v[154:157], v[66:81]
	ds_read_b128 v[82:85], v246 offset:128
	v_exp_f32_e32 v164, v40
	v_exp_f32_e32 v142, v41
	ds_read_b128 v[38:41], v250 offset:12288
	v_exp_f32_e32 v244, v54
	v_exp_f32_e32 v170, v55
	v_exp_f32_e32 v166, v56
	v_mfma_f32_32x32x16_bf16 v[66:81], v[86:89], v[158:161], v[66:81]
	ds_read_b128 v[86:89], v246 offset:160
	ds_read_b128 v[50:53], v248 offset:12288
	v_exp_f32_e32 v144, v57
	v_exp_f32_e32 v136, v42
	v_exp_f32_e32 v140, v58
	v_exp_f32_e32 v128, v43
	v_exp_f32_e32 v132, v59
	s_waitcnt lgkmcnt(1)
	v_mfma_f32_32x32x16_bf16 v[82:97], v[34:37], v[146:149], v[82:97]
	ds_read_b128 v[34:37], v249 offset:12288
	v_exp_f32_e32 v120, v44
	v_exp_f32_e32 v124, v60
	v_exp_f32_e32 v114, v45
	v_exp_f32_e32 v118, v61
	v_exp_f32_e32 v110, v46
	v_exp_f32_e32 v112, v62
	s_waitcnt lgkmcnt(1)
	v_mfma_f32_32x32x16_bf16 v[82:97], v[50:53], v[150:153], v[82:97]
	v_exp_f32_e32 v104, v47
	v_exp_f32_e32 v108, v63
	v_exp_f32_e32 v102, v48
	v_exp_f32_e32 v98, v49
	v_exp_f32_e32 v106, v64
	v_exp_f32_e32 v100, v65
	s_waitcnt lgkmcnt(0)
	v_mfma_f32_32x32x16_bf16 v[82:97], v[34:37], v[154:157], v[82:97]
	v_mfma_f32_32x32x16_bf16 v[82:97], v[38:41], v[158:161], v[82:97]
	v_cvt_pk_bf16_f32 v213, v126, v116
	v_cvt_pk_bf16_f32 v214, v186, v168
	v_cvt_pk_bf16_f32 v215, v164, v142
	v_cvt_pk_bf16_f32 v174, v136, v128
	v_cvt_pk_bf16_f32 v175, v120, v114
	v_cvt_pk_bf16_f32 v176, v110, v104
	v_cvt_pk_bf16_f32 v177, v102, v98
	v_cvt_pk_bf16_f32 v178, v162, v138
	v_cvt_pk_bf16_f32 v179, v130, v172
	v_cvt_pk_bf16_f32 v180, v244, v170
	v_cvt_pk_bf16_f32 v181, v166, v144
	v_cvt_pk_bf16_f32 v208, v140, v132
	v_cvt_pk_bf16_f32 v209, v124, v118
	v_cvt_pk_bf16_f32 v210, v112, v108
	v_cvt_pk_bf16_f32 v211, v106, v100
	v_cvt_pk_bf16_f32 v212, v122, v134
	ds_read_b64_tr_b16 v[50:51], v0 offset:16384
	ds_read_b64_tr_b16 v[52:53], v0 offset:16896
	ds_read_b64_tr_b16 v[216:217], v0 offset:20480
	ds_read_b64_tr_b16 v[218:219], v0 offset:20992
	v_exp_f32_e32 v123, v66
	v_exp_f32_e32 v163, v82
	v_exp_f32_e32 v135, v67
	v_exp_f32_e32 v139, v83
	v_exp_f32_e32 v127, v68
	v_exp_f32_e32 v187, v70
	v_exp_f32_e32 v245, v86
	v_exp_f32_e32 v131, v84
	v_exp_f32_e32 v117, v69
	v_exp_f32_e32 v173, v85
	v_exp_f32_e32 v169, v71
	v_exp_f32_e32 v165, v72
	v_exp_f32_e32 v143, v73
	v_exp_f32_e32 v137, v74
	v_exp_f32_e32 v129, v75
	v_exp_f32_e32 v121, v76
	v_exp_f32_e32 v115, v77
	v_exp_f32_e32 v111, v78
	v_exp_f32_e32 v105, v79
	v_exp_f32_e32 v103, v80
	v_exp_f32_e32 v99, v81
	ds_read_b64_tr_b16 v[220:221], v0 offset:17408
	ds_read_b64_tr_b16 v[222:223], v0 offset:17920
	ds_read_b64_tr_b16 v[224:225], v0 offset:21504
	ds_read_b64_tr_b16 v[226:227], v0 offset:22016
	ds_read_b64_tr_b16 v[228:229], v0 offset:18432
	ds_read_b64_tr_b16 v[230:231], v0 offset:18944
	ds_read_b64_tr_b16 v[232:233], v0 offset:22528
	ds_read_b64_tr_b16 v[234:235], v0 offset:23040
	ds_read_b64_tr_b16 v[236:237], v0 offset:19456
	ds_read_b64_tr_b16 v[238:239], v0 offset:19968
	ds_read_b64_tr_b16 v[240:241], v0 offset:23552
	ds_read_b64_tr_b16 v[242:243], v0 offset:24064
	s_waitcnt lgkmcnt(14)
	v_mfma_f32_32x32x16_bf16 v[34:49], v[212:215], v[50:53], v[18:33]
	v_add_f32_e64 v66, v186, v244
	v_add_f32_e64 v67, v187, v245
	v_cvt_pk_bf16_f32 v68, v123, v135
	v_cvt_pk_bf16_f32 v69, v127, v117
	v_cvt_pk_bf16_f32 v70, v187, v169
	v_cvt_pk_bf16_f32 v71, v165, v143
	v_cvt_pk_bf16_f32 v72, v137, v129
	v_cvt_pk_bf16_f32 v73, v121, v115
	v_cvt_pk_bf16_f32 v74, v111, v105
	v_cvt_pk_bf16_f32 v75, v103, v99
	v_cvt_pk_bf16_f32 v76, v163, v139
	v_cvt_pk_bf16_f32 v77, v131, v173
	s_waitcnt lgkmcnt(12)
	v_mfma_f32_32x32x16_bf16 v[50:65], v[212:215], v[216:219], v[2:17]
	v_exp_f32_e32 v171, v87
	v_exp_f32_e32 v167, v88
	v_exp_f32_e32 v145, v89
	v_exp_f32_e32 v141, v90
	v_exp_f32_e32 v133, v91
	v_exp_f32_e32 v125, v92
	v_exp_f32_e32 v119, v93
	v_exp_f32_e32 v113, v94
	v_exp_f32_e32 v109, v95
	v_exp_f32_e32 v107, v96
	v_exp_f32_e32 v101, v97
	v_cvt_pk_bf16_f32 v78, v245, v171
	v_cvt_pk_bf16_f32 v79, v167, v145
	v_cvt_pk_bf16_f32 v80, v141, v133
	v_cvt_pk_bf16_f32 v81, v125, v119
	v_cvt_pk_bf16_f32 v82, v113, v109
	v_cvt_pk_bf16_f32 v83, v107, v101
	s_waitcnt lgkmcnt(10)
	v_mfma_f32_32x32x16_bf16 v[34:49], v[174:177], v[220:223], v[34:49]
	v_add_f32_e64 v84, v122, v162
	v_add_f32_e64 v85, v123, v163
	v_add_f32_e64 v86, v134, v138
	v_add_f32_e64 v87, v135, v139
	v_add_f32_e64 v84, v84, 0
	v_add_f32_e64 v85, v85, 0
	v_add_f32_e32 v88, v126, v130
	v_add_f32_e32 v89, v127, v131
	v_add_f32_e32 v84, v86, v84
	v_add_f32_e32 v85, v87, v85
	v_add_f32_e32 v90, v116, v172
	v_add_f32_e32 v91, v117, v173
	v_add_f32_e32 v84, v88, v84
	v_add_f32_e32 v85, v89, v85
	s_waitcnt lgkmcnt(8)
	v_mfma_f32_32x32x16_bf16 v[50:65], v[174:177], v[224:227], v[50:65]
	v_add_f32_e64 v84, v90, v84
	v_add_f32_e64 v85, v91, v85
	v_add_f32_e64 v86, v168, v170
	v_add_f32_e64 v87, v169, v171
	v_add_f32_e64 v66, v66, v84
	v_add_f32_e64 v67, v67, v85
	v_add_f32_e32 v88, v164, v166
	v_add_f32_e32 v89, v165, v167
	v_add_f32_e32 v66, v86, v66
	v_add_f32_e32 v67, v87, v67
	v_add_f32_e32 v90, v142, v144
	v_add_f32_e32 v91, v143, v145
	v_add_f32_e32 v66, v88, v66
	v_add_f32_e32 v67, v89, v67
	s_waitcnt lgkmcnt(6)
	v_mfma_f32_32x32x16_bf16 v[34:49], v[178:181], v[228:231], v[34:49]
	v_add_f32_e64 v92, v136, v140
	v_add_f32_e64 v93, v137, v141
	v_add_f32_e64 v66, v90, v66
	v_add_f32_e64 v67, v91, v67
	v_add_f32_e64 v94, v128, v132
	v_add_f32_e64 v95, v129, v133
	v_add_f32_e32 v66, v92, v66
	v_add_f32_e32 v67, v93, v67
	v_add_f32_e32 v96, v120, v124
	v_add_f32_e32 v97, v121, v125
	v_add_f32_e32 v66, v94, v66
	v_add_f32_e32 v67, v95, v67
	v_add_f32_e32 v114, v114, v118
	v_add_f32_e32 v115, v115, v119
	s_waitcnt lgkmcnt(4)
	v_mfma_f32_32x32x16_bf16 v[50:65], v[178:181], v[232:235], v[50:65]
	v_add_f32_e64 v66, v96, v66
	v_add_f32_e64 v67, v97, v67
	v_add_f32_e64 v110, v110, v112
	v_add_f32_e64 v111, v111, v113
	v_add_f32_e64 v66, v114, v66
	v_add_f32_e64 v67, v115, v67
	v_add_f32_e32 v104, v104, v108
	v_add_f32_e32 v105, v105, v109
	v_add_f32_e32 v66, v110, v66
	v_add_f32_e32 v67, v111, v67
	v_add_f32_e32 v102, v102, v106
	v_add_f32_e32 v103, v103, v107
	v_add_f32_e32 v66, v104, v66
	v_add_f32_e32 v67, v105, v67
	s_waitcnt lgkmcnt(2)
	v_mfma_f32_32x32x16_bf16 v[34:49], v[208:211], v[236:239], v[34:49]
	v_add_f32_e64 v98, v98, v100
	v_add_f32_e64 v99, v99, v101
	v_add_f32_e64 v66, v102, v66
	v_add_f32_e64 v67, v103, v67
	v_add_f32_e64 v66, v98, v66
	v_add_f32_e64 v67, v99, v67
	v_add_f32_e32 v66, v205, v66
	s_waitcnt lgkmcnt(0)
	v_mfma_f32_32x32x16_bf16 v[50:65], v[208:211], v[240:243], v[50:65]
	v_add_f32_e32 v66, v66, v67
	ds_read_b64_tr_b16 v[84:85], v0 offset:24576
	ds_read_b64_tr_b16 v[86:87], v0 offset:25088
	ds_read_b64_tr_b16 v[88:89], v0 offset:25600
	ds_read_b64_tr_b16 v[90:91], v0 offset:26112
	s_waitcnt lgkmcnt(2)
	v_mfma_f32_32x32x16_bf16 v[34:49], v[68:71], v[84:87], v[34:49]
	ds_read_b64_tr_b16 v[84:85], v0 offset:28672
	ds_read_b64_tr_b16 v[86:87], v0 offset:29184
	ds_read_b64_tr_b16 v[92:93], v0 offset:29696
	ds_read_b64_tr_b16 v[94:95], v0 offset:30208
	s_waitcnt lgkmcnt(2)
	v_mfma_f32_32x32x16_bf16 v[50:65], v[68:71], v[84:87], v[50:65]
	ds_read_b64_tr_b16 v[68:69], v0 offset:26624
	ds_read_b64_tr_b16 v[70:71], v0 offset:27136
	ds_read_b64_tr_b16 v[84:85], v0 offset:31744
	ds_read_b64_tr_b16 v[86:87], v0 offset:32256
	v_mfma_f32_32x32x16_bf16 v[34:49], v[72:75], v[88:91], v[34:49]
	s_waitcnt lgkmcnt(4)
	v_mfma_f32_32x32x16_bf16 v[50:65], v[72:75], v[92:95], v[50:65]
	ds_read_b64_tr_b16 v[72:73], v0 offset:27648
	ds_read_b64_tr_b16 v[74:75], v0 offset:28160
	s_waitcnt lgkmcnt(4)
	v_mfma_f32_32x32x16_bf16 v[34:49], v[76:79], v[68:71], v[34:49]
	ds_read_b64_tr_b16 v[68:69], v0 offset:30720
	ds_read_b64_tr_b16 v[70:71], v0 offset:31232
	s_waitcnt lgkmcnt(0)
	v_mfma_f32_32x32x16_bf16 v[50:65], v[76:79], v[68:71], v[50:65]
	v_mfma_f32_32x32x16_bf16 v[34:49], v[80:83], v[72:75], v[34:49]
	v_mfma_f32_32x32x16_bf16 v[50:65], v[80:83], v[84:87], v[50:65]
